# x_init row loop: 4 row loads issued together with counted vmcnt (was 4 serialized load-convert-store round trips per row)
# baseline (speedup 1.0000x reference)
; __device__ __forceinline__ unsigned cvt_pk_bf16(float lo, float hi) { unsigned r; asm volatile("v_cvt_pk_bf16_f32 %0, %1, %2" : "=v"(r) : "v"(lo), "v"(hi)); return r; }
; __device__ __forceinline__ unsigned pack4_fp8(float a, float b, float c, float d) { unsigned w = 0u; w = __builtin_amdgcn_cvt_pk_fp8_f32(a, b, w, false); w = __builtin_amdgcn_cvt_pk_fp8_f32(c, d, w, true); return w; }
; __device__ __forceinline__ void x_init(const Params& P) {
;     ...
;     for (int row = gw; row < T_TOK; row += nw) { float ss = 0.f;
; #pragma unroll
;         for (int k = 0; k < 4; ++k) { const size_t o = (size_t)row * 1024 + k * 256 + lane * 4; const f32x4 v = *(const f32x4*)(P.x + o);
;             u32x2 w; w.x = cvt_pk_bf16(v[0], v[1]); w.y = cvt_pk_bf16(v[2], v[3]); *(u32x2*)(xb0 + o) = w;
;             *(unsigned*)(P.ws + OFF_ZB + (size_t)row * (ZW * 2) + k * 256 + lane * 4) = pack4_fp8(v[0], v[1], v[2], v[3]); ss += (v[0] * v[0] + v[1] * v[1]) + (v[2] * v[2] + v[3] * v[3]); }
; #pragma unroll
;         for (int o = 32; o >= 1; o >>= 1) ss += __shfl_xor(ss, o);
;         if (lane < 16) ssq0[((size_t)(lane >> 2) * T_TOK + row) * 4 + (lane & 3)] = lane == 0 ? ss : 0.f; }
.LBB0_8:
	s_waitcnt lgkmcnt(0)
	global_load_dwordx4 v[18:21], v[10:11], off offset:-2048
	global_load_dwordx4 v[22:25], v[10:11], off offset:-1024
	global_load_dwordx4 v[26:29], v[10:11], off
	global_load_dwordx4 v[30:33], v[10:11], off offset:1024
	v_lshl_add_u64 v[72:73], s[14:15], 0, v[8:9]
	v_add_co_u32_e32 v34, vcc, 0x6800000, v72
	s_nop 1
	v_addc_co_u32_e32 v35, vcc, 0, v73, vcc
	v_lshl_add_u64 v[72:73], s[14:15], 0, v[6:7]
	v_add_co_u32_e32 v36, vcc, 0xae00000, v72
	s_nop 1
	v_addc_co_u32_e32 v37, vcc, 0, v73, vcc
	v_mov_b32_e32 v68, 0
	v_mov_b32_e32 v69, 0
	v_mov_b32_e32 v70, 0
	v_mov_b32_e32 v71, 0
	s_waitcnt vmcnt(3)
	v_cvt_pk_bf16_f32 v60, v18, v19
	v_cvt_pk_bf16_f32 v61, v20, v21
	v_cvt_pk_fp8_f32 v68, v18, v19
	v_mul_f32_e32 v19, v19, v19
	v_fmac_f32_e32 v19, v18, v18
	v_cvt_pk_fp8_f32 v68, v20, v21 op_sel:[0,0,1]
	v_mul_f32_e32 v21, v21, v21
	v_fmac_f32_e32 v21, v20, v20
	global_store_dwordx2 v[34:35], v[60:61], off
	global_store_dword v[36:37], v68, off
	v_add_f32_e32 v18, v19, v21
	s_waitcnt vmcnt(4)
	v_cvt_pk_bf16_f32 v62, v22, v23
	v_cvt_pk_bf16_f32 v63, v24, v25
	v_cvt_pk_fp8_f32 v69, v22, v23
	v_mul_f32_e32 v19, v23, v23
	v_mul_f32_e32 v20, v25, v25
	v_fmac_f32_e32 v19, v22, v22
	v_cvt_pk_fp8_f32 v69, v24, v25 op_sel:[0,0,1]
	v_fmac_f32_e32 v20, v24, v24
	v_add_f32_e32 v19, v19, v20
	global_store_dwordx2 v[34:35], v[62:63], off offset:512
	global_store_dword v[36:37], v69, off offset:256
	v_add_f32_e32 v18, v18, v19
	s_waitcnt vmcnt(5)
	v_cvt_pk_bf16_f32 v64, v26, v27
	v_cvt_pk_bf16_f32 v65, v28, v29
	v_cvt_pk_fp8_f32 v70, v26, v27
	v_mul_f32_e32 v19, v27, v27
	v_mul_f32_e32 v20, v29, v29
	v_fmac_f32_e32 v19, v26, v26
	v_cvt_pk_fp8_f32 v70, v28, v29 op_sel:[0,0,1]
	v_fmac_f32_e32 v20, v28, v28
	v_add_f32_e32 v19, v19, v20
	global_store_dwordx2 v[34:35], v[64:65], off offset:1024
	global_store_dword v[36:37], v70, off offset:512
	v_add_f32_e32 v18, v18, v19
	s_waitcnt vmcnt(6)
	v_cvt_pk_bf16_f32 v66, v30, v31
	v_cvt_pk_bf16_f32 v67, v32, v33
	v_cvt_pk_fp8_f32 v71, v30, v31
	v_mul_f32_e32 v19, v31, v31
	v_mul_f32_e32 v20, v33, v33
	v_fmac_f32_e32 v19, v30, v30
	v_cvt_pk_fp8_f32 v71, v32, v33 op_sel:[0,0,1]
	v_fmac_f32_e32 v20, v32, v32
	v_add_f32_e32 v19, v19, v20
	global_store_dwordx2 v[34:35], v[66:67], off offset:1536
	global_store_dword v[36:37], v71, off offset:768
	v_add_f32_e32 v18, v18, v19
	v_cmp_lt_i32_e32 vcc, v12, v3
	s_nop 1
	v_cndmask_b32_e32 v20, v1, v12, vcc
	v_lshlrev_b32_e32 v20, 2, v20
	ds_bpermute_b32 v19, v20, v18
	s_waitcnt lgkmcnt(0)
	v_add_f32_e32 v18, v18, v19
	v_cmp_lt_i32_e32 vcc, v13, v3
	s_nop 1
	v_cndmask_b32_e32 v20, v1, v13, vcc
	v_lshlrev_b32_e32 v20, 2, v20
	ds_bpermute_b32 v19, v20, v18
	s_waitcnt lgkmcnt(0)
	v_add_f32_e32 v18, v18, v19
	v_cmp_lt_i32_e32 vcc, v14, v3
	s_nop 1
	v_cndmask_b32_e32 v20, v1, v14, vcc
	v_lshlrev_b32_e32 v20, 2, v20
	ds_bpermute_b32 v19, v20, v18
	s_waitcnt lgkmcnt(0)
	v_add_f32_e32 v18, v18, v19
	v_cmp_lt_i32_e32 vcc, v15, v3
	s_nop 1
	v_cndmask_b32_e32 v20, v1, v15, vcc
	v_lshlrev_b32_e32 v20, 2, v20
	ds_bpermute_b32 v19, v20, v18
	s_waitcnt lgkmcnt(0)
	v_add_f32_e32 v18, v18, v19
	v_cmp_lt_i32_e32 vcc, v16, v3
	s_nop 1
	v_cndmask_b32_e32 v20, v1, v16, vcc
	v_lshlrev_b32_e32 v20, 2, v20
	ds_bpermute_b32 v19, v20, v18
	s_waitcnt lgkmcnt(0)
	v_add_f32_e32 v18, v18, v19
	v_cmp_lt_i32_e32 vcc, v17, v3
	s_nop 1
	v_cndmask_b32_e32 v20, v1, v17, vcc
	v_lshlrev_b32_e32 v20, 2, v20
	ds_bpermute_b32 v19, v20, v18
	s_and_saveexec_b64 s[28:29], s[8:9]
	s_cbranch_execz .LBB0_7
	s_waitcnt lgkmcnt(0)
	v_add_f32_e32 v18, v18, v19
	v_lshl_add_u64 v[20:21], s[14:15], 0, v[4:5]
	v_cndmask_b32_e64 v18, 0, v18, s[10:11]
	global_store_dword v[20:21], v18, off
	s_branch .LBB0_7
